# attention unmasked loop: one static priority raise for waves 4-7 instead of per-iteration setprio toggles
# speedup vs baseline: 1.0060x; 1.0060x over previous
; #define A_LOAD(t) do { _Pragma("unroll") for (int j_ = 0; j_ < 2; ++j_) { kreg[j_] = *(const u32x4*)(kg + (size_t)(64 * (t) + 32 * j_) * NIN); vreg[j_] = *(const u32x4*)(kg + 512 + (size_t)(64 * (t) + 32 * j_) * NIN); } } while (0)
; #define A_STORE(kbi, vbi) do { _Pragma("unroll") for (int j_ = 0; j_ < 2; ++j_) { *(LAS u32x4*)(lds + A_K0 + (kbi) * KBUF + (skey + 32 * j_) * KSTR + sch * 16) = kreg[j_]; *(LAS u32x4*)(lds + A_V0 + (vbi) * VBUF + (skey + 32 * j_) * VSTR + sch * 16) = vreg[j_]; } } while (0)
; #define A_FIRST(MASKED, t) do { A_QK(t) \
;             EX4(p0, 0); EX4(p0, 4); EX4(p0, 8); EX4(p0, 12); EX4(p1, 0); EX4(p1, 4); EX4(p1, 8); EX4(p1, 12); \
;             if (MASKED) { A_MASK(p0, t, 0); A_MASK(p1, t, 32); } \
;             SUM8(p0, 0); SUM8(p0, 8); SUM8(p1, 0); SUM8(p1, 8); \
;             PK4(pwp0, p0, 0); PK4(pwp1, p0, 8); PK4(pwp2, p1, 0); PK4(pwp3, p1, 8); } while (0)
; __device__ __forceinline__ void attn_phase(LAS unsigned char* lds, const AttnArgs& a, int tid_in) {
;     ...
;         f32x16 cinit;
; #pragma unroll
;         for (int r = 0; r < 16; ++r) cinit[r] = -a.shift;
;         asm volatile("" : "+v"(cinit));
;         asm volatile("" : "+v"(qr[0]), "+v"(qr[1]), "+v"(qr[2]), "+v"(qr[3]));
;         const int NTM = (2 * qb) < NT ? (2 * qb) : NT;
;         u32x4 pwp0, pwp1, pwp2, pwp3;
;         if (NTM == 0) A_FIRST(true, 0); else A_FIRST(false, 0);
;         A_STORE(1, 1);
;         if (2 < NT) A_LOAD(2);
;         __syncthreads();
;         int t = 1, vp = 0, vn = 2;
.LBB0_578:
	v_cvt_pk_bf16_f32 v179, v14, v15
	s_cmp_lt_i32 s35, 2
	s_mov_b32 s34, 2
	s_waitcnt lgkmcnt(0)
	s_barrier
	s_cbranch_scc1 .LBB0_583
	v_mov_b32_e32 v64, 0
	s_mov_b32 s6, 0
	s_mov_b32 s4, 1
	s_movk_i32 s5, 0xe0
	v_mov_b32_e32 v65, v64
	v_mov_b32_e32 v66, v64
	v_mov_b32_e32 v67, v64
	v_mov_b32_e32 v68, v64
	v_mov_b32_e32 v69, v64
	v_mov_b32_e32 v70, v64
	v_mov_b32_e32 v71, v64
	v_mov_b32_e32 v72, v64
	v_mov_b32_e32 v73, v64
	v_mov_b32_e32 v74, v64
	v_mov_b32_e32 v75, v64
	v_mov_b32_e32 v76, v64
	v_mov_b32_e32 v77, v64
	v_mov_b32_e32 v78, v64
	v_mov_b32_e32 v79, v64
	v_mov_b32_e32 v80, v64
	v_mov_b32_e32 v81, v64
	v_mov_b32_e32 v82, v64
	v_mov_b32_e32 v83, v64
	v_mov_b32_e32 v84, v64
	v_mov_b32_e32 v85, v64
	v_mov_b32_e32 v86, v64
	v_mov_b32_e32 v87, v64
	v_mov_b32_e32 v88, v64
	v_mov_b32_e32 v89, v64
	v_mov_b32_e32 v90, v64
	v_mov_b32_e32 v91, v64
	v_mov_b32_e32 v92, v64
	v_mov_b32_e32 v93, v64
	v_mov_b32_e32 v94, v64
	v_mov_b32_e32 v95, v64
	v_mov_b32_e32 v48, v64
	v_mov_b32_e32 v49, v64
	v_mov_b32_e32 v50, v64
	v_mov_b32_e32 v51, v64
	v_mov_b32_e32 v52, v64
	v_mov_b32_e32 v53, v64
	v_mov_b32_e32 v54, v64
	v_mov_b32_e32 v55, v64
	v_mov_b32_e32 v56, v64
	v_mov_b32_e32 v57, v64
	v_mov_b32_e32 v58, v64
	v_mov_b32_e32 v59, v64
	v_mov_b32_e32 v60, v64
	v_mov_b32_e32 v61, v64
	v_mov_b32_e32 v62, v64
	v_mov_b32_e32 v63, v64
	v_mov_b32_e32 v32, v64
	v_mov_b32_e32 v33, v64
	v_mov_b32_e32 v34, v64
	v_mov_b32_e32 v35, v64
	v_mov_b32_e32 v36, v64
	v_mov_b32_e32 v37, v64
	v_mov_b32_e32 v38, v64
	v_mov_b32_e32 v39, v64
	v_mov_b32_e32 v40, v64
	v_mov_b32_e32 v41, v64
	v_mov_b32_e32 v42, v64
	v_mov_b32_e32 v43, v64
	v_mov_b32_e32 v44, v64
	v_mov_b32_e32 v45, v64
	v_mov_b32_e32 v46, v64
	v_mov_b32_e32 v47, v64
	v_readfirstlane_b32 s30, v193
	s_lshr_b32 s30, s30, 8
	s_cmp_eq_u32 s30, 0
	s_cbranch_scc1 .Lattn_prio_skip
	s_setprio 1

.LBB0_581:
	s_nop 0
	s_bitcmp1_b32 s4, 0
	s_cselect_b32 s30, 0x4400, 0
	v_add_u32_e32 v0, s30, v224
	ds_read_b128 v[2:5], v0
	ds_read_b128 v[6:9], v0 offset:32
	s_mul_i32 s30, s6, 0x5000
	s_waitcnt lgkmcnt(1)
	v_mfma_f32_32x32x16_bf16 v[128:143], v[2:5], v[144:147], v[96:111]
	ds_read_b128 v[2:5], v0 offset:8704
	ds_read_b128 v[10:13], v0 offset:8736
	s_waitcnt lgkmcnt(1)
	v_mfma_f32_32x32x16_bf16 v[112:127], v[2:5], v[144:147], v[96:111]
	v_mfma_f32_32x32x16_bf16 v[128:143], v[6:9], v[148:151], v[128:143]
	ds_read_b128 v[2:5], v0 offset:64
	ds_read_b128 v[6:9], v0 offset:96
	s_waitcnt lgkmcnt(2)
	v_mfma_f32_32x32x16_bf16 v[112:127], v[10:13], v[148:151], v[112:127]
	s_waitcnt lgkmcnt(1)
	v_mfma_f32_32x32x16_bf16 v[128:143], v[2:5], v[152:155], v[128:143]
	ds_read_b128 v[2:5], v0 offset:8768
	ds_read_b128 v[10:13], v0 offset:8800
	v_add_u32_e32 v0, s30, v225
	s_waitcnt lgkmcnt(1)
	v_mfma_f32_32x32x16_bf16 v[112:127], v[2:5], v[152:155], v[112:127]
	v_mfma_f32_32x32x16_bf16 v[128:143], v[6:9], v[156:159], v[128:143]
	ds_read_b64_tr_b16 v[2:3], v0 offset:34816
	ds_read_b64_tr_b16 v[6:7], v0 offset:34880
	ds_read_b64_tr_b16 v[236:237], v0 offset:34944
	ds_read_b64_tr_b16 v[240:241], v0 offset:35008
	ds_read_b64_tr_b16 v[4:5], v0 offset:37376
	ds_read_b64_tr_b16 v[8:9], v0 offset:37440
	ds_read_b64_tr_b16 v[238:239], v0 offset:37504
	ds_read_b64_tr_b16 v[242:243], v0 offset:37568
	s_waitcnt lgkmcnt(8)
	v_mfma_f32_32x32x16_bf16 v[112:127], v[10:13], v[156:159], v[112:127]
	s_waitcnt lgkmcnt(3)
	v_mfma_f32_32x32x16_bf16 v[64:79], v[188:191], v[2:5], v[64:79]
	ds_read_b64_tr_b16 v[2:3], v0 offset:39936
	ds_read_b64_tr_b16 v[4:5], v0 offset:42496
	v_exp_f32_e32 v128, v128
	v_exp_f32_e32 v129, v129
	v_exp_f32_e32 v130, v130
	v_add_f32_e32 v17, v128, v129
	s_waitcnt lgkmcnt(4)
	v_mfma_f32_32x32x16_bf16 v[80:95], v[188:191], v[6:9], v[80:95]
	ds_read_b64_tr_b16 v[6:7], v0 offset:40000
	ds_read_b64_tr_b16 v[8:9], v0 offset:42560
	v_exp_f32_e32 v131, v131
	v_exp_f32_e32 v132, v132
	v_exp_f32_e32 v133, v133
	v_add_f32_e32 v17, v17, v130
	s_waitcnt lgkmcnt(5)
	v_mfma_f32_32x32x16_bf16 v[48:63], v[188:191], v[236:239], v[48:63]
	ds_read_b64_tr_b16 v[10:11], v0 offset:40064
	ds_read_b64_tr_b16 v[12:13], v0 offset:42624
	v_exp_f32_e32 v134, v134
	v_exp_f32_e32 v135, v135
	v_exp_f32_e32 v136, v136
	v_add_f32_e32 v17, v17, v131
	s_waitcnt lgkmcnt(6)
	v_mfma_f32_32x32x16_bf16 v[32:47], v[188:191], v[240:243], v[32:47]
	ds_read_b64_tr_b16 v[28:29], v0 offset:40128
	ds_read_b64_tr_b16 v[30:31], v0 offset:42688
	v_exp_f32_e32 v137, v137
	v_exp_f32_e32 v138, v138
	v_exp_f32_e32 v139, v139
	v_cvt_pk_bf16_f32 v188, v128, v129
	s_waitcnt lgkmcnt(6)
	v_mfma_f32_32x32x16_bf16 v[64:79], v[184:187], v[2:5], v[64:79]
	ds_read_b64_tr_b16 v[2:3], v0 offset:45056
	ds_read_b64_tr_b16 v[4:5], v0 offset:47616
	v_exp_f32_e32 v140, v140
	v_exp_f32_e32 v141, v141
	v_exp_f32_e32 v142, v142
	v_cvt_pk_bf16_f32 v189, v130, v131
	s_waitcnt lgkmcnt(6)
	v_mfma_f32_32x32x16_bf16 v[80:95], v[184:187], v[6:9], v[80:95]
	ds_read_b64_tr_b16 v[6:7], v0 offset:45120
	ds_read_b64_tr_b16 v[8:9], v0 offset:47680
	v_exp_f32_e32 v143, v143
	v_exp_f32_e32 v112, v112
	v_exp_f32_e32 v113, v113
	v_cvt_pk_bf16_f32 v190, v132, v133
	s_waitcnt lgkmcnt(6)
	v_mfma_f32_32x32x16_bf16 v[48:63], v[184:187], v[10:13], v[48:63]
	ds_read_b64_tr_b16 v[10:11], v0 offset:45184
	ds_read_b64_tr_b16 v[12:13], v0 offset:47744
	v_exp_f32_e32 v114, v114
	v_exp_f32_e32 v115, v115
	v_exp_f32_e32 v116, v116
	v_cvt_pk_bf16_f32 v191, v134, v135
	s_waitcnt lgkmcnt(6)
	v_mfma_f32_32x32x16_bf16 v[32:47], v[184:187], v[28:31], v[32:47]
	ds_read_b64_tr_b16 v[28:29], v0 offset:45248
	ds_read_b64_tr_b16 v[30:31], v0 offset:47808
	s_andn2_b32 s30, 1, s4
	s_mulk_i32 s30, 0x4400
	s_mul_i32 s31, s34, 0x5000
	v_add3_u32 v21, v223, s30, v228
	v_add3_u32 v22, v223, s31, v229
	v_exp_f32_e32 v117, v117
	v_exp_f32_e32 v118, v118
	v_exp_f32_e32 v119, v119
	v_cvt_pk_bf16_f32 v184, v136, v137
	s_waitcnt lgkmcnt(6)
	v_mfma_f32_32x32x16_bf16 v[64:79], v[180:183], v[2:5], v[64:79]
	ds_read_b64_tr_b16 v[2:3], v0 offset:50176
	ds_read_b64_tr_b16 v[4:5], v0 offset:52736
	s_waitcnt vmcnt(3)
	ds_write_b128 v21, v[160:163]
	v_exp_f32_e32 v120, v120
	v_exp_f32_e32 v121, v121
	v_exp_f32_e32 v122, v122
	v_cvt_pk_bf16_f32 v185, v138, v139
	s_waitcnt lgkmcnt(7)
	v_mfma_f32_32x32x16_bf16 v[80:95], v[180:183], v[6:9], v[80:95]
	ds_read_b64_tr_b16 v[6:7], v0 offset:50240
	ds_read_b64_tr_b16 v[8:9], v0 offset:52800
	s_waitcnt vmcnt(2)
	ds_write_b128 v22, v[164:167] offset:34816
	v_exp_f32_e32 v123, v123
	v_exp_f32_e32 v124, v124
	v_exp_f32_e32 v125, v125
	v_cvt_pk_bf16_f32 v186, v140, v141
	s_waitcnt lgkmcnt(8)
	v_mfma_f32_32x32x16_bf16 v[48:63], v[180:183], v[10:13], v[48:63]
	ds_read_b64_tr_b16 v[10:11], v0 offset:50304
	ds_read_b64_tr_b16 v[12:13], v0 offset:52864
	s_waitcnt vmcnt(1)
	ds_write_b128 v21, v[168:171] offset:8704
	v_exp_f32_e32 v126, v126
	v_exp_f32_e32 v127, v127
	v_cvt_pk_bf16_f32 v187, v142, v143
	v_add_f32_e32 v17, v17, v132
	v_add_f32_e32 v17, v17, v133
	s_waitcnt lgkmcnt(9)
	v_mfma_f32_32x32x16_bf16 v[32:47], v[180:183], v[28:31], v[32:47]
	ds_read_b64_tr_b16 v[28:29], v0 offset:50368
	ds_read_b64_tr_b16 v[30:31], v0 offset:52928
	s_waitcnt vmcnt(0)
	ds_write_b128 v22, v[172:175] offset:45056
	v_cvt_pk_bf16_f32 v180, v112, v113
	v_cvt_pk_bf16_f32 v181, v114, v115
	v_cvt_pk_bf16_f32 v182, v116, v117
	v_cvt_pk_bf16_f32 v183, v118, v119
	v_add_f32_e32 v17, v17, v134
	v_add_f32_e32 v17, v17, v135
	v_add_f32_e32 v18, v136, v137
	s_waitcnt lgkmcnt(10)
	v_mfma_f32_32x32x16_bf16 v[64:79], v[176:179], v[2:5], v[64:79]
	v_add_f32_e32 v18, v18, v138
	v_add_f32_e32 v18, v18, v139
	v_add_f32_e32 v18, v18, v140
	v_add_f32_e32 v18, v18, v141
	v_add_f32_e32 v18, v18, v142
	v_add_f32_e32 v18, v18, v143
	v_add_f32_e32 v19, v112, v113
	s_waitcnt lgkmcnt(7)
	v_mfma_f32_32x32x16_bf16 v[80:95], v[176:179], v[6:9], v[80:95]
	v_add_f32_e32 v19, v19, v114
	v_add_f32_e32 v19, v19, v115
	v_add_f32_e32 v19, v19, v116
	v_add_f32_e32 v19, v19, v117
	v_add_f32_e32 v19, v19, v118
	v_add_f32_e32 v19, v19, v119
	v_add_f32_e32 v20, v120, v121
	s_add_i32 s30, s4, 2
	s_cmp_ge_i32 s30, s27
	s_cbranch_scc1 .Lattn_u_skipld
	s_sub_i32 s30, s5, 32
	v_mad_u64_u32 v[24:25], s[30:31], s30, v219, v[202:203]
	v_mad_u64_u32 v[26:27], s[30:31], s5, v219, v[202:203]
	global_load_dwordx4 v[160:163], v[24:25], off
	global_load_dwordx4 v[164:167], v[24:25], off offset:1024
	global_load_dwordx4 v[168:171], v[26:27], off
	global_load_dwordx4 v[172:175], v[26:27], off offset:1024
; #define A_LOAD(t) do { _Pragma("unroll") for (int j_ = 0; j_ < 2; ++j_) { kreg[j_] = *(const u32x4*)(kg + (size_t)(64 * (t) + 32 * j_) * NIN); vreg[j_] = *(const u32x4*)(kg + 512 + (size_t)(64 * (t) + 32 * j_) * NIN); } } while (0)
; #define A_STORE(kbi, vbi) do { _Pragma("unroll") for (int j_ = 0; j_ < 2; ++j_) { *(LAS u32x4*)(lds + A_K0 + (kbi) * KBUF + (skey + 32 * j_) * KSTR + sch * 16) = kreg[j_]; *(LAS u32x4*)(lds + A_V0 + (vbi) * VBUF + (skey + 32 * j_) * VSTR + sch * 16) = vreg[j_]; } } while (0)
; __device__ __forceinline__ void attn_phase(LAS unsigned char* lds, const AttnArgs& a, int tid_in) {
;     ...
;             A_STORE((t + 1) & 1, vn);
;             if (t + 2 < NT) A_LOAD(t + 2);
;             __syncthreads();
;             vp = (vp == 2) ? 0 : vp + 1; vn = (vn == 2) ? 0 : vn + 1;
;         }
.Lattn_u_skipld:
	s_waitcnt lgkmcnt(4)
	v_mfma_f32_32x32x16_bf16 v[48:63], v[176:179], v[10:13], v[48:63]
	v_add_f32_e32 v20, v20, v122
	v_add_f32_e32 v20, v20, v123
	v_add_f32_e32 v20, v20, v124
	v_add_f32_e32 v20, v20, v125
	v_add_f32_e32 v20, v20, v126
	v_add_f32_e32 v20, v20, v127
	v_add_f32_e32 v17, v17, v18
	s_waitcnt lgkmcnt(1)
	v_mfma_f32_32x32x16_bf16 v[32:47], v[176:179], v[28:31], v[32:47]
	v_cvt_pk_bf16_f32 v176, v120, v121
	v_cvt_pk_bf16_f32 v177, v122, v123
	v_cvt_pk_bf16_f32 v178, v124, v125
	v_cvt_pk_bf16_f32 v179, v126, v127
	v_add_f32_e32 v19, v19, v20
	v_add_f32_e32 v17, v17, v19
	v_add_f32_e32 v211, v211, v17
	s_nop 0
	s_add_i32 s30, s6, 1
	s_cmp_lg_u32 s6, 2
	s_cselect_b32 s6, s30, 0
	s_add_i32 s30, s34, 1
	s_cmp_lg_u32 s34, 2
	s_cselect_b32 s34, s30, 0
	s_add_i32 s4, s4, 1
	s_add_i32 s5, s5, 64
	s_cmp_eq_u32 s35, s4
	s_waitcnt lgkmcnt(0)
	s_barrier
	s_cbranch_scc0 .LBB0_581
	s_setprio 0
	s_branch .LBB0_584
